# speedup vs baseline: 1.0057x; 1.0057x over previous
; __device__ __forceinline__ float bf2f(bf16_t b) { return __uint_as_float(((unsigned)b) << 16); }
; __device__ __forceinline__ void gla_gate(unsigned char* lds, const bf16_t* P, const float* wgu, const float* bgt, int row0, int nvalid, int h, float (&bc)[16], float& blast) {
;     ...
;     { const bf16_t* gp = P + (size_t)row0 * NPROJ + C_GL;
;       for (int idx = tid; idx < 1024; idx += 512) { const int t = idx >> 4, r = idx & 15; gl[idx] = (t < nvalid) ? bf2f(gp[t * NPROJ + r]) : 0.f; } }
;     float wg[16];
;     { const float* wp = wgu + h * 128;
; #pragma unroll
;       for (int r = 0; r < 16; ++r) wg[r] = wp[r * 512 + kd]; }
;     const float bg = bgt[h * 128 + kd];
;     __syncthreads();
;     float run = 0.f;
; #pragma unroll
;     for (int i = 0; i < 16; ++i) {
;         const int t = tq * 16 + i; float x = bg;
;         const f32x4* g4 = (const f32x4*)(gl + t * 16);
; #pragma unroll
;         for (int r4 = 0; r4 < 4; ++r4) { const f32x4 gv = g4[r4];
; #pragma unroll
;             for (int e = 0; e < 4; ++e) x += gv[e] * wg[4 * r4 + e]; }
;         float lg = fminf(x, 0.f) - __logf(1.f + __expf(-fabsf(x)));
;         lg = (t < nvalid) ? lg * (1.f / 16.f) : 0.f;
;         run += lg; bc[i] = run;
;     }
.LBB0_969:
	s_or_b64 exec, exec, s[0:1]
	s_lshr_b32 s14, s20, 6
	s_and_b64 s[0:1], s[10:11], exec
	s_cselect_b32 s0, s20, s14
	s_and_b32 s15, s0, 3
	v_readlane_b32 s56, v251, 18
	s_ashr_i32 s14, s90, 7
	s_lshl_b32 s16, s15, 9
	v_readlane_b32 s70, v251, 32
	v_readlane_b32 s71, v251, 33
	s_add_u32 s0, s70, s16
	v_lshlrev_b32_e32 v0, 2, v0
	s_addc_u32 s1, s71, 0
	v_and_b32_e32 v36, 0x1fc, v0
	v_lshl_add_u64 v[16:17], s[0:1], 0, v[36:37]
	v_add_co_u32_e32 v2, vcc, s30, v16
	global_load_dword v1, v36, s[0:1]
	global_load_dword v0, v36, s[0:1] offset:2048
	v_addc_co_u32_e32 v3, vcc, 0, v17, vcc
	s_movk_i32 s0, 0x2000
	v_add_co_u32_e32 v6, vcc, s0, v16
	s_movk_i32 s0, 0x3000
	s_nop 0
	v_addc_co_u32_e32 v7, vcc, 0, v17, vcc
	v_add_co_u32_e32 v8, vcc, s0, v16
	s_movk_i32 s0, 0x4000
	s_nop 0
	v_addc_co_u32_e32 v9, vcc, 0, v17, vcc
	v_add_co_u32_e32 v10, vcc, s0, v16
	s_movk_i32 s0, 0x5000
	s_nop 0
	v_addc_co_u32_e32 v11, vcc, 0, v17, vcc
	global_load_dword v5, v[6:7], off offset:-4096
	global_load_dword v4, v[2:3], off offset:2048
	s_nop 0
	global_load_dword v3, v[6:7], off
	global_load_dword v2, v[6:7], off offset:2048
	s_nop 0
	global_load_dword v7, v[10:11], off offset:-4096
	global_load_dword v6, v[8:9], off offset:2048
	s_nop 0
	global_load_dword v9, v[10:11], off
	global_load_dword v8, v[10:11], off offset:2048
	v_add_co_u32_e32 v10, vcc, s0, v16
	s_movk_i32 s0, 0x6000
	s_nop 0
	v_addc_co_u32_e32 v11, vcc, 0, v17, vcc
	v_add_co_u32_e32 v18, vcc, s0, v16
	s_movk_i32 s0, 0x7000
	s_nop 0
	v_addc_co_u32_e32 v19, vcc, 0, v17, vcc
	v_readlane_b32 s57, v251, 19
	v_readlane_b32 s58, v251, 20
	v_readlane_b32 s59, v251, 21
	v_readlane_b32 s60, v251, 22
	v_readlane_b32 s61, v251, 23
	v_readlane_b32 s62, v251, 24
	v_readlane_b32 s63, v251, 25
	v_readlane_b32 s64, v251, 26
	v_readlane_b32 s65, v251, 27
	v_readlane_b32 s66, v251, 28
	v_readlane_b32 s67, v251, 29
	v_readlane_b32 s68, v251, 30
	v_readlane_b32 s69, v251, 31
	v_add_co_u32_e32 v16, vcc, s0, v16
	v_readlane_b32 s56, v251, 34
	s_nop 0
	v_addc_co_u32_e32 v17, vcc, 0, v17, vcc
	global_load_dword v14, v[18:19], off offset:-4096
	global_load_dword v12, v[10:11], off offset:2048
	s_nop 0
	global_load_dword v11, v[18:19], off
	global_load_dword v10, v[18:19], off offset:2048
	global_load_dword v15, v[16:17], off
	global_load_dword v13, v[16:17], off offset:2048
	v_or_b32_e32 v16, s16, v36
	v_readlane_b32 s57, v251, 35
	s_lshl_b32 s0, s14, 10
	s_add_i32 s0, s0, 0
	v_mov_b32_e32 v17, s0
	s_lshl_b32 s16, s14, 4
	s_cmp_lt_i32 s16, s84
	global_load_dword v16, v16, s[56:57]
	s_waitcnt lgkmcnt(0)
	s_barrier
	ds_read_b128 v[18:21], v17
	ds_read_b128 v[22:25], v17 offset:16
	ds_read_b128 v[26:29], v17 offset:32
	ds_read_b128 v[30:33], v17 offset:48
	v_readlane_b32 s56, v251, 50
	v_readlane_b32 s57, v251, 51
	v_readlane_b32 s58, v251, 36
	v_readlane_b32 s59, v251, 37
	v_readlane_b32 s60, v251, 38
	v_readlane_b32 s61, v251, 39
	v_readlane_b32 s62, v251, 40
	v_readlane_b32 s63, v251, 41
	v_readlane_b32 s64, v251, 42
	v_readlane_b32 s65, v251, 43
	v_readlane_b32 s66, v251, 44
	v_readlane_b32 s67, v251, 45
	v_readlane_b32 s68, v251, 46
	v_readlane_b32 s69, v251, 47
	v_readlane_b32 s70, v251, 48
	v_readlane_b32 s71, v251, 49
	s_waitcnt vmcnt(0) lgkmcnt(3)
	v_fma_f32 v17, v1, v18, v16
	v_fmac_f32_e32 v17, v0, v19
	v_fmac_f32_e32 v17, v5, v20
	v_fmac_f32_e32 v17, v4, v21
	s_waitcnt lgkmcnt(2)
	v_fmac_f32_e32 v17, v3, v22
	v_fmac_f32_e32 v17, v2, v23
	v_fmac_f32_e32 v17, v7, v24
	v_fmac_f32_e32 v17, v6, v25
	s_waitcnt lgkmcnt(1)
	v_fmac_f32_e32 v17, v9, v26
	v_fmac_f32_e32 v17, v8, v27
	v_fmac_f32_e32 v17, v14, v28
	v_fmac_f32_e32 v17, v12, v29
	s_waitcnt lgkmcnt(0)
	v_fmac_f32_e32 v17, v11, v30
	v_fmac_f32_e32 v17, v10, v31
	v_fmac_f32_e32 v17, v15, v32
	v_fmac_f32_e32 v17, v13, v33
	v_min_f32_e32 v18, 0, v17
	v_mul_f32_e64 v17, |v17|, s31
	v_exp_f32_e32 v17, v17
	s_nop 0
	v_add_f32_e32 v17, 1.0, v17
	v_cmp_gt_f32_e32 vcc, s38, v17
	s_nop 1
	v_cndmask_b32_e64 v19, 0, 32, vcc
	v_ldexp_f32 v17, v17, v19
	v_log_f32_e32 v17, v17
	s_nop 0
	v_mul_f32_e32 v19, 0x3f317217, v17
	v_fma_f32 v19, v17, s39, -v19
	v_fmac_f32_e32 v19, 0x3377d1cf, v17
	v_fmac_f32_e32 v19, 0x3f317217, v17
	v_cmp_lt_f32_e64 s[0:1], |v17|, s27
	s_nop 1
	v_cndmask_b32_e64 v17, v17, v19, s[0:1]
	v_cndmask_b32_e32 v19, 0, v48, vcc
	s_cselect_b64 vcc, -1, 0
	s_or_b32 s17, s16, 1
	s_lshl_b32 s0, s17, 6
	s_add_i32 s0, s0, 0
	v_sub_f32_e32 v17, v17, v19
	v_mov_b32_e32 v30, s0
	v_sub_f32_e32 v17, v18, v17
	ds_read_b128 v[18:21], v30
	ds_read_b128 v[22:25], v30 offset:16
	ds_read_b128 v[26:29], v30 offset:32
	ds_read_b128 v[30:33], v30 offset:48
	v_fma_f32 v17, v17, s28, 0
	s_waitcnt lgkmcnt(3)
	v_fma_f32 v18, v1, v18, v16
	v_fmac_f32_e32 v18, v0, v19
	v_fmac_f32_e32 v18, v5, v20
	v_fmac_f32_e32 v18, v4, v21
	s_waitcnt lgkmcnt(2)
	v_fmac_f32_e32 v18, v3, v22
	v_fmac_f32_e32 v18, v2, v23
	v_fmac_f32_e32 v18, v7, v24
	v_fmac_f32_e32 v18, v6, v25
	s_waitcnt lgkmcnt(1)
	v_fmac_f32_e32 v18, v9, v26
	v_fmac_f32_e32 v18, v8, v27
	v_fmac_f32_e32 v18, v14, v28
	v_fmac_f32_e32 v18, v12, v29
	s_waitcnt lgkmcnt(0)
	v_fmac_f32_e32 v18, v11, v30
	v_fmac_f32_e32 v18, v10, v31
	v_fmac_f32_e32 v18, v15, v32
	v_fmac_f32_e32 v18, v13, v33
	v_min_f32_e32 v19, 0, v18
	v_mul_f32_e64 v18, |v18|, s31
	v_exp_f32_e32 v18, v18
	v_cndmask_b32_e32 v17, 0, v17, vcc
	s_cmp_lt_i32 s17, s84
	v_add_f32_e32 v18, 1.0, v18
	v_cmp_gt_f32_e32 vcc, s38, v18
	s_nop 1
	v_cndmask_b32_e64 v20, 0, 32, vcc
	v_ldexp_f32 v18, v18, v20
	v_log_f32_e32 v18, v18
	s_nop 0
	v_mul_f32_e32 v20, 0x3f317217, v18
	v_fma_f32 v20, v18, s39, -v20
	v_fmac_f32_e32 v20, 0x3377d1cf, v18
	v_fmac_f32_e32 v20, 0x3f317217, v18
	v_cmp_lt_f32_e64 s[0:1], |v18|, s27
	s_nop 1
	v_cndmask_b32_e64 v18, v18, v20, s[0:1]
	v_cndmask_b32_e32 v20, 0, v48, vcc
	s_cselect_b64 vcc, -1, 0
	s_or_b32 s17, s16, 2
	s_lshl_b32 s0, s17, 6
	v_sub_f32_e32 v18, v18, v20
	s_add_i32 s0, s0, 0
	v_sub_f32_e32 v18, v19, v18
	v_mov_b32_e32 v19, s0
	ds_read_b128 v[20:23], v19
	ds_read_b128 v[24:27], v19 offset:16
	ds_read_b128 v[28:31], v19 offset:32
	ds_read_b128 v[32:35], v19 offset:48
	v_mul_f32_e32 v18, 0x3d800000, v18
	s_waitcnt lgkmcnt(3)
; __device__ __forceinline__ void gla_gate(unsigned char* lds, const bf16_t* P, const float* wgu, const float* bgt, int row0, int nvalid, int h, float (&bc)[16], float& blast) {
;     ...
;     for (int i = 0; i < 16; ++i) {
;         const int t = tq * 16 + i; float x = bg;
;         const f32x4* g4 = (const f32x4*)(gl + t * 16);
; #pragma unroll
;         for (int r4 = 0; r4 < 4; ++r4) { const f32x4 gv = g4[r4];
; #pragma unroll
;             for (int e = 0; e < 4; ++e) x += gv[e] * wg[4 * r4 + e]; }
;         float lg = fminf(x, 0.f) - __logf(1.f + __expf(-fabsf(x)));
;         lg = (t < nvalid) ? lg * (1.f / 16.f) : 0.f;
;         run += lg; bc[i] = run;
	v_fma_f32 v19, v1, v20, v16
	v_fmac_f32_e32 v19, v0, v21
	v_fmac_f32_e32 v19, v5, v22
	v_fmac_f32_e32 v19, v4, v23
	s_waitcnt lgkmcnt(2)
	v_fmac_f32_e32 v19, v3, v24
	v_fmac_f32_e32 v19, v2, v25
	v_fmac_f32_e32 v19, v7, v26
	v_fmac_f32_e32 v19, v6, v27
	s_waitcnt lgkmcnt(1)
	v_fmac_f32_e32 v19, v9, v28
	v_fmac_f32_e32 v19, v8, v29
	v_fmac_f32_e32 v19, v14, v30
	v_fmac_f32_e32 v19, v12, v31
	s_waitcnt lgkmcnt(0)
	v_fmac_f32_e32 v19, v11, v32
	v_fmac_f32_e32 v19, v10, v33
	v_fmac_f32_e32 v19, v15, v34
	v_fmac_f32_e32 v19, v13, v35
	v_min_f32_e32 v20, 0, v19
	v_mul_f32_e64 v19, |v19|, s31
	v_exp_f32_e32 v19, v19
	v_cndmask_b32_e32 v18, 0, v18, vcc
	s_cmp_lt_i32 s17, s84
	v_add_f32_e32 v18, v17, v18
	v_add_f32_e32 v19, 1.0, v19
	v_cmp_gt_f32_e32 vcc, s38, v19
	s_nop 1
	v_cndmask_b32_e64 v21, 0, 32, vcc
	v_ldexp_f32 v19, v19, v21
	v_log_f32_e32 v19, v19
	s_nop 0
	v_mul_f32_e32 v21, 0x3f317217, v19
	v_fma_f32 v21, v19, s39, -v21
	v_fmac_f32_e32 v21, 0x3377d1cf, v19
	v_fmac_f32_e32 v21, 0x3f317217, v19
	v_cmp_lt_f32_e64 s[0:1], |v19|, s27
	s_nop 1
	v_cndmask_b32_e64 v19, v19, v21, s[0:1]
	v_cndmask_b32_e32 v21, 0, v48, vcc
	s_cselect_b64 vcc, -1, 0
	s_or_b32 s17, s16, 3
	s_lshl_b32 s0, s17, 6
	s_add_i32 s0, s0, 0
	v_sub_f32_e32 v19, v19, v21
	v_mov_b32_e32 v32, s0
	v_sub_f32_e32 v19, v20, v19
	ds_read_b128 v[20:23], v32
	ds_read_b128 v[24:27], v32 offset:16
	ds_read_b128 v[28:31], v32 offset:32
	ds_read_b128 v[32:35], v32 offset:48
	v_mul_f32_e32 v19, 0x3d800000, v19
	s_waitcnt lgkmcnt(3)
	v_fma_f32 v20, v1, v20, v16
	v_fmac_f32_e32 v20, v0, v21
	v_fmac_f32_e32 v20, v5, v22
	v_fmac_f32_e32 v20, v4, v23
	s_waitcnt lgkmcnt(2)
	v_fmac_f32_e32 v20, v3, v24
	v_fmac_f32_e32 v20, v2, v25
	v_fmac_f32_e32 v20, v7, v26
	v_fmac_f32_e32 v20, v6, v27
	s_waitcnt lgkmcnt(1)
	v_fmac_f32_e32 v20, v9, v28
	v_fmac_f32_e32 v20, v8, v29
	v_fmac_f32_e32 v20, v14, v30
	v_fmac_f32_e32 v20, v12, v31
	s_waitcnt lgkmcnt(0)
	v_fmac_f32_e32 v20, v11, v32
	v_fmac_f32_e32 v20, v10, v33
	v_fmac_f32_e32 v20, v15, v34
	v_fmac_f32_e32 v20, v13, v35
	v_min_f32_e32 v21, 0, v20
	v_mul_f32_e64 v20, |v20|, s31
	v_exp_f32_e32 v20, v20
	v_cndmask_b32_e32 v19, 0, v19, vcc
	s_cmp_lt_i32 s17, s84
	v_add_f32_e32 v19, v18, v19
	v_add_f32_e32 v20, 1.0, v20
	v_cmp_gt_f32_e32 vcc, s38, v20
	s_nop 1
	v_cndmask_b32_e64 v22, 0, 32, vcc
	v_ldexp_f32 v20, v20, v22
	v_log_f32_e32 v20, v20
	s_nop 0
	v_mul_f32_e32 v22, 0x3f317217, v20
	v_fma_f32 v22, v20, s39, -v22
	v_fmac_f32_e32 v22, 0x3377d1cf, v20
	v_fmac_f32_e32 v22, 0x3f317217, v20
	v_cmp_lt_f32_e64 s[0:1], |v20|, s27
	s_nop 1
	v_cndmask_b32_e64 v20, v20, v22, s[0:1]
	v_cndmask_b32_e32 v22, 0, v48, vcc
	s_cselect_b64 vcc, -1, 0
	s_or_b32 s17, s16, 4
	s_lshl_b32 s0, s17, 6
	v_sub_f32_e32 v20, v20, v22
	s_add_i32 s0, s0, 0
	v_sub_f32_e32 v20, v21, v20
	v_mov_b32_e32 v21, s0
	ds_read_b128 v[22:25], v21
	ds_read_b128 v[26:29], v21 offset:16
	ds_read_b128 v[30:33], v21 offset:32
	ds_read_b128 v[38:41], v21 offset:48
	v_mul_f32_e32 v20, 0x3d800000, v20
	s_waitcnt lgkmcnt(3)
	v_fma_f32 v21, v1, v22, v16
	v_fmac_f32_e32 v21, v0, v23
	v_fmac_f32_e32 v21, v5, v24
	v_fmac_f32_e32 v21, v4, v25
	s_waitcnt lgkmcnt(2)
	v_fmac_f32_e32 v21, v3, v26
	v_fmac_f32_e32 v21, v2, v27
	v_fmac_f32_e32 v21, v7, v28
	v_fmac_f32_e32 v21, v6, v29
	s_waitcnt lgkmcnt(1)
	v_fmac_f32_e32 v21, v9, v30
	v_fmac_f32_e32 v21, v8, v31
	v_fmac_f32_e32 v21, v14, v32
	v_fmac_f32_e32 v21, v12, v33
	s_waitcnt lgkmcnt(0)
	v_fmac_f32_e32 v21, v11, v38
	v_fmac_f32_e32 v21, v10, v39
	v_fmac_f32_e32 v21, v15, v40
	v_fmac_f32_e32 v21, v13, v41
	v_min_f32_e32 v22, 0, v21
	v_mul_f32_e64 v21, |v21|, s31
	v_exp_f32_e32 v21, v21
	v_cndmask_b32_e32 v20, 0, v20, vcc
	s_cmp_lt_i32 s17, s84
	v_add_f32_e32 v20, v19, v20
	v_add_f32_e32 v21, 1.0, v21
	v_cmp_gt_f32_e32 vcc, s38, v21
	s_nop 1
	v_cndmask_b32_e64 v23, 0, 32, vcc
	v_ldexp_f32 v21, v21, v23
	v_log_f32_e32 v21, v21
	s_nop 0
	v_mul_f32_e32 v23, 0x3f317217, v21
	v_fma_f32 v23, v21, s39, -v23
	v_fmac_f32_e32 v23, 0x3377d1cf, v21
	v_fmac_f32_e32 v23, 0x3f317217, v21
	v_cmp_lt_f32_e64 s[0:1], |v21|, s27
	s_nop 1
	v_cndmask_b32_e64 v21, v21, v23, s[0:1]
	v_cndmask_b32_e32 v23, 0, v48, vcc
	s_cselect_b64 vcc, -1, 0
	s_or_b32 s17, s16, 5
	s_lshl_b32 s0, s17, 6
	s_add_i32 s0, s0, 0
	v_sub_f32_e32 v21, v21, v23
	v_mov_b32_e32 v34, s0
	v_sub_f32_e32 v21, v22, v21
	ds_read_b128 v[22:25], v34
	ds_read_b128 v[26:29], v34 offset:16
	ds_read_b128 v[30:33], v34 offset:32
	ds_read_b128 v[38:41], v34 offset:48
	v_mul_f32_e32 v21, 0x3d800000, v21
	s_waitcnt lgkmcnt(3)
	v_fma_f32 v22, v1, v22, v16
	v_fmac_f32_e32 v22, v0, v23
	v_fmac_f32_e32 v22, v5, v24
	v_fmac_f32_e32 v22, v4, v25
	s_waitcnt lgkmcnt(2)
	v_fmac_f32_e32 v22, v3, v26
	v_fmac_f32_e32 v22, v2, v27
	v_fmac_f32_e32 v22, v7, v28
	v_fmac_f32_e32 v22, v6, v29
	s_waitcnt lgkmcnt(1)
	v_fmac_f32_e32 v22, v9, v30
	v_fmac_f32_e32 v22, v8, v31
	v_fmac_f32_e32 v22, v14, v32
	v_fmac_f32_e32 v22, v12, v33
	s_waitcnt lgkmcnt(0)
	v_fmac_f32_e32 v22, v11, v38
	v_fmac_f32_e32 v22, v10, v39
	v_fmac_f32_e32 v22, v15, v40
	v_fmac_f32_e32 v22, v13, v41
	v_min_f32_e32 v23, 0, v22
	v_mul_f32_e64 v22, |v22|, s31
	v_exp_f32_e32 v22, v22
	v_cndmask_b32_e32 v21, 0, v21, vcc
	s_cmp_lt_i32 s17, s84
	v_add_f32_e32 v21, v20, v21
	v_add_f32_e32 v22, 1.0, v22
	v_cmp_gt_f32_e32 vcc, s38, v22
	s_nop 1
	v_cndmask_b32_e64 v24, 0, 32, vcc
	v_ldexp_f32 v22, v22, v24
	v_log_f32_e32 v22, v22
	s_nop 0
	v_mul_f32_e32 v24, 0x3f317217, v22
	v_fma_f32 v24, v22, s39, -v24
	v_fmac_f32_e32 v24, 0x3377d1cf, v22
	v_fmac_f32_e32 v24, 0x3f317217, v22
	v_cmp_lt_f32_e64 s[0:1], |v22|, s27
	s_nop 1
	v_cndmask_b32_e64 v22, v22, v24, s[0:1]
	v_cndmask_b32_e32 v24, 0, v48, vcc
	s_cselect_b64 vcc, -1, 0
	s_or_b32 s17, s16, 6
	s_lshl_b32 s0, s17, 6
	v_sub_f32_e32 v22, v22, v24
	s_add_i32 s0, s0, 0
	v_sub_f32_e32 v22, v23, v22
	v_mov_b32_e32 v23, s0
	ds_read_b128 v[24:27], v23
	ds_read_b128 v[28:31], v23 offset:16
	ds_read_b128 v[32:35], v23 offset:32
	ds_read_b128 v[38:41], v23 offset:48
	v_mul_f32_e32 v22, 0x3d800000, v22
	s_waitcnt lgkmcnt(3)
; __device__ __forceinline__ void gla_gate(unsigned char* lds, const bf16_t* P, const float* wgu, const float* bgt, int row0, int nvalid, int h, float (&bc)[16], float& blast) {
;     ...
;     for (int i = 0; i < 16; ++i) {
;         const int t = tq * 16 + i; float x = bg;
;         const f32x4* g4 = (const f32x4*)(gl + t * 16);
; #pragma unroll
;         for (int r4 = 0; r4 < 4; ++r4) { const f32x4 gv = g4[r4];
; #pragma unroll
;             for (int e = 0; e < 4; ++e) x += gv[e] * wg[4 * r4 + e]; }
;         float lg = fminf(x, 0.f) - __logf(1.f + __expf(-fabsf(x)));
;         lg = (t < nvalid) ? lg * (1.f / 16.f) : 0.f;
;         run += lg; bc[i] = run;
	v_fma_f32 v23, v1, v24, v16
	v_fmac_f32_e32 v23, v0, v25
	v_fmac_f32_e32 v23, v5, v26
	v_fmac_f32_e32 v23, v4, v27
	s_waitcnt lgkmcnt(2)
	v_fmac_f32_e32 v23, v3, v28
	v_fmac_f32_e32 v23, v2, v29
	v_fmac_f32_e32 v23, v7, v30
	v_fmac_f32_e32 v23, v6, v31
	s_waitcnt lgkmcnt(1)
	v_fmac_f32_e32 v23, v9, v32
	v_fmac_f32_e32 v23, v8, v33
	v_fmac_f32_e32 v23, v14, v34
	v_fmac_f32_e32 v23, v12, v35
	s_waitcnt lgkmcnt(0)
	v_fmac_f32_e32 v23, v11, v38
	v_fmac_f32_e32 v23, v10, v39
	v_fmac_f32_e32 v23, v15, v40
	v_fmac_f32_e32 v23, v13, v41
	v_min_f32_e32 v24, 0, v23
	v_mul_f32_e64 v23, |v23|, s31
	v_exp_f32_e32 v23, v23
	v_cndmask_b32_e32 v22, 0, v22, vcc
	s_cmp_lt_i32 s17, s84
	v_add_f32_e32 v22, v21, v22
	v_add_f32_e32 v23, 1.0, v23
	v_cmp_gt_f32_e32 vcc, s38, v23
	s_nop 1
	v_cndmask_b32_e64 v25, 0, 32, vcc
	v_ldexp_f32 v23, v23, v25
	v_log_f32_e32 v23, v23
	s_nop 0
	v_mul_f32_e32 v25, 0x3f317217, v23
	v_fma_f32 v25, v23, s39, -v25
	v_fmac_f32_e32 v25, 0x3377d1cf, v23
	v_fmac_f32_e32 v25, 0x3f317217, v23
	v_cmp_lt_f32_e64 s[0:1], |v23|, s27
	s_nop 1
	v_cndmask_b32_e64 v23, v23, v25, s[0:1]
	v_cndmask_b32_e32 v25, 0, v48, vcc
	s_cselect_b64 vcc, -1, 0
	s_or_b32 s17, s16, 7
	s_lshl_b32 s0, s17, 6
	s_add_i32 s0, s0, 0
	v_sub_f32_e32 v23, v23, v25
	v_mov_b32_e32 v38, s0
	v_sub_f32_e32 v23, v24, v23
	ds_read_b128 v[24:27], v38
	ds_read_b128 v[28:31], v38 offset:16
	ds_read_b128 v[32:35], v38 offset:32
	ds_read_b128 v[38:41], v38 offset:48
	v_mul_f32_e32 v23, 0x3d800000, v23
	s_waitcnt lgkmcnt(3)
	v_fma_f32 v24, v1, v24, v16
	v_fmac_f32_e32 v24, v0, v25
	v_fmac_f32_e32 v24, v5, v26
	v_fmac_f32_e32 v24, v4, v27
	s_waitcnt lgkmcnt(2)
	v_fmac_f32_e32 v24, v3, v28
	v_fmac_f32_e32 v24, v2, v29
	v_fmac_f32_e32 v24, v7, v30
	v_fmac_f32_e32 v24, v6, v31
	s_waitcnt lgkmcnt(1)
	v_fmac_f32_e32 v24, v9, v32
	v_fmac_f32_e32 v24, v8, v33
	v_fmac_f32_e32 v24, v14, v34
	v_fmac_f32_e32 v24, v12, v35
	s_waitcnt lgkmcnt(0)
	v_fmac_f32_e32 v24, v11, v38
	v_fmac_f32_e32 v24, v10, v39
	v_fmac_f32_e32 v24, v15, v40
	v_fmac_f32_e32 v24, v13, v41
	v_min_f32_e32 v25, 0, v24
	v_mul_f32_e64 v24, |v24|, s31
	v_exp_f32_e32 v24, v24
	v_cndmask_b32_e32 v23, 0, v23, vcc
	s_cmp_lt_i32 s17, s84
	v_add_f32_e32 v23, v22, v23
	v_add_f32_e32 v24, 1.0, v24
	v_cmp_gt_f32_e32 vcc, s38, v24
	s_nop 1
	v_cndmask_b32_e64 v26, 0, 32, vcc
	v_ldexp_f32 v24, v24, v26
	v_log_f32_e32 v24, v24
	s_nop 0
	v_mul_f32_e32 v26, 0x3f317217, v24
	v_fma_f32 v26, v24, s39, -v26
	v_fmac_f32_e32 v26, 0x3377d1cf, v24
	v_fmac_f32_e32 v26, 0x3f317217, v24
	v_cmp_lt_f32_e64 s[0:1], |v24|, s27
	s_nop 1
	v_cndmask_b32_e64 v24, v24, v26, s[0:1]
	v_cndmask_b32_e32 v26, 0, v48, vcc
	s_cselect_b64 vcc, -1, 0
	s_or_b32 s17, s16, 8
	s_lshl_b32 s0, s17, 6
	v_sub_f32_e32 v24, v24, v26
	s_add_i32 s0, s0, 0
	v_sub_f32_e32 v24, v25, v24
	v_mov_b32_e32 v25, s0
	ds_read_b128 v[26:29], v25
	ds_read_b128 v[30:33], v25 offset:16
	ds_read_b128 v[38:41], v25 offset:32
	ds_read_b128 v[42:45], v25 offset:48
	v_mul_f32_e32 v24, 0x3d800000, v24
	s_waitcnt lgkmcnt(3)
	v_fma_f32 v25, v1, v26, v16
	v_fmac_f32_e32 v25, v0, v27
	v_fmac_f32_e32 v25, v5, v28
	v_fmac_f32_e32 v25, v4, v29
	s_waitcnt lgkmcnt(2)
	v_fmac_f32_e32 v25, v3, v30
	v_fmac_f32_e32 v25, v2, v31
	v_fmac_f32_e32 v25, v7, v32
	v_fmac_f32_e32 v25, v6, v33
	s_waitcnt lgkmcnt(1)
	v_fmac_f32_e32 v25, v9, v38
	v_fmac_f32_e32 v25, v8, v39
	v_fmac_f32_e32 v25, v14, v40
	v_fmac_f32_e32 v25, v12, v41
	s_waitcnt lgkmcnt(0)
	v_fmac_f32_e32 v25, v11, v42
	v_fmac_f32_e32 v25, v10, v43
	v_fmac_f32_e32 v25, v15, v44
	v_fmac_f32_e32 v25, v13, v45
	v_min_f32_e32 v26, 0, v25
	v_mul_f32_e64 v25, |v25|, s31
	v_exp_f32_e32 v25, v25
	v_cndmask_b32_e32 v24, 0, v24, vcc
	s_cmp_lt_i32 s17, s84
	v_add_f32_e32 v24, v23, v24
	v_add_f32_e32 v25, 1.0, v25
	v_cmp_gt_f32_e32 vcc, s38, v25
	s_nop 1
	v_cndmask_b32_e64 v27, 0, 32, vcc
	v_ldexp_f32 v25, v25, v27
	v_log_f32_e32 v25, v25
	s_nop 0
	v_mul_f32_e32 v27, 0x3f317217, v25
	v_fma_f32 v27, v25, s39, -v27
	v_fmac_f32_e32 v27, 0x3377d1cf, v25
	v_fmac_f32_e32 v27, 0x3f317217, v25
	v_cmp_lt_f32_e64 s[0:1], |v25|, s27
	s_nop 1
	v_cndmask_b32_e64 v25, v25, v27, s[0:1]
	v_cndmask_b32_e32 v27, 0, v48, vcc
	s_cselect_b64 vcc, -1, 0
	s_or_b32 s17, s16, 9
	s_lshl_b32 s0, s17, 6
	s_add_i32 s0, s0, 0
	v_sub_f32_e32 v25, v25, v27
	v_mov_b32_e32 v34, s0
	v_sub_f32_e32 v25, v26, v25
	ds_read_b128 v[26:29], v34
	ds_read_b128 v[30:33], v34 offset:16
	ds_read_b128 v[38:41], v34 offset:32
	ds_read_b128 v[42:45], v34 offset:48
	v_mul_f32_e32 v25, 0x3d800000, v25
	s_waitcnt lgkmcnt(3)
	v_fma_f32 v26, v1, v26, v16
	v_fmac_f32_e32 v26, v0, v27
	v_fmac_f32_e32 v26, v5, v28
	v_fmac_f32_e32 v26, v4, v29
	s_waitcnt lgkmcnt(2)
	v_fmac_f32_e32 v26, v3, v30
	v_fmac_f32_e32 v26, v2, v31
	v_fmac_f32_e32 v26, v7, v32
	v_fmac_f32_e32 v26, v6, v33
	s_waitcnt lgkmcnt(1)
	v_fmac_f32_e32 v26, v9, v38
	v_fmac_f32_e32 v26, v8, v39
	v_fmac_f32_e32 v26, v14, v40
	v_fmac_f32_e32 v26, v12, v41
	s_waitcnt lgkmcnt(0)
	v_fmac_f32_e32 v26, v11, v42
	v_fmac_f32_e32 v26, v10, v43
	v_fmac_f32_e32 v26, v15, v44
	v_fmac_f32_e32 v26, v13, v45
	v_min_f32_e32 v27, 0, v26
	v_mul_f32_e64 v26, |v26|, s31
	v_exp_f32_e32 v26, v26
	v_cndmask_b32_e32 v25, 0, v25, vcc
	s_cmp_lt_i32 s17, s84
	v_add_f32_e32 v25, v24, v25
	v_add_f32_e32 v26, 1.0, v26
	v_cmp_gt_f32_e32 vcc, s38, v26
	s_nop 1
	v_cndmask_b32_e64 v28, 0, 32, vcc
	v_ldexp_f32 v26, v26, v28
	v_log_f32_e32 v26, v26
	s_nop 0
	v_mul_f32_e32 v28, 0x3f317217, v26
	v_fma_f32 v28, v26, s39, -v28
	v_fmac_f32_e32 v28, 0x3377d1cf, v26
	v_fmac_f32_e32 v28, 0x3f317217, v26
	v_cmp_lt_f32_e64 s[0:1], |v26|, s27
	s_nop 1
	v_cndmask_b32_e64 v26, v26, v28, s[0:1]
	v_cndmask_b32_e32 v28, 0, v48, vcc
	s_cselect_b64 vcc, -1, 0
	s_or_b32 s17, s16, 10
	s_lshl_b32 s0, s17, 6
	v_sub_f32_e32 v26, v26, v28
	s_add_i32 s0, s0, 0
	v_sub_f32_e32 v26, v27, v26
	v_mov_b32_e32 v27, s0
	ds_read_b128 v[28:31], v27
	ds_read_b128 v[32:35], v27 offset:16
	ds_read_b128 v[38:41], v27 offset:32
	ds_read_b128 v[42:45], v27 offset:48
	v_mul_f32_e32 v26, 0x3d800000, v26
	s_waitcnt lgkmcnt(3)
; __device__ __forceinline__ void gla_gate(unsigned char* lds, const bf16_t* P, const float* wgu, const float* bgt, int row0, int nvalid, int h, float (&bc)[16], float& blast) {
;     ...
;     for (int i = 0; i < 16; ++i) {
;         const int t = tq * 16 + i; float x = bg;
;         const f32x4* g4 = (const f32x4*)(gl + t * 16);
; #pragma unroll
;         for (int r4 = 0; r4 < 4; ++r4) { const f32x4 gv = g4[r4];
; #pragma unroll
;             for (int e = 0; e < 4; ++e) x += gv[e] * wg[4 * r4 + e]; }
;         float lg = fminf(x, 0.f) - __logf(1.f + __expf(-fabsf(x)));
;         lg = (t < nvalid) ? lg * (1.f / 16.f) : 0.f;
;         run += lg; bc[i] = run;
	v_fma_f32 v27, v1, v28, v16
	v_fmac_f32_e32 v27, v0, v29
	v_fmac_f32_e32 v27, v5, v30
	v_fmac_f32_e32 v27, v4, v31
	s_waitcnt lgkmcnt(2)
	v_fmac_f32_e32 v27, v3, v32
	v_fmac_f32_e32 v27, v2, v33
	v_fmac_f32_e32 v27, v7, v34
	v_fmac_f32_e32 v27, v6, v35
	s_waitcnt lgkmcnt(1)
	v_fmac_f32_e32 v27, v9, v38
	v_fmac_f32_e32 v27, v8, v39
	v_fmac_f32_e32 v27, v14, v40
	v_fmac_f32_e32 v27, v12, v41
	s_waitcnt lgkmcnt(0)
	v_fmac_f32_e32 v27, v11, v42
	v_fmac_f32_e32 v27, v10, v43
	v_fmac_f32_e32 v27, v15, v44
	v_fmac_f32_e32 v27, v13, v45
	v_min_f32_e32 v28, 0, v27
	v_mul_f32_e64 v27, |v27|, s31
	v_exp_f32_e32 v27, v27
	v_cndmask_b32_e32 v26, 0, v26, vcc
	s_cmp_lt_i32 s17, s84
	v_add_f32_e32 v26, v25, v26
	v_add_f32_e32 v27, 1.0, v27
	v_cmp_gt_f32_e32 vcc, s38, v27
	s_nop 1
	v_cndmask_b32_e64 v29, 0, 32, vcc
	v_ldexp_f32 v27, v27, v29
	v_log_f32_e32 v27, v27
	s_nop 0
	v_mul_f32_e32 v29, 0x3f317217, v27
	v_fma_f32 v29, v27, s39, -v29
	v_fmac_f32_e32 v29, 0x3377d1cf, v27
	v_fmac_f32_e32 v29, 0x3f317217, v27
	v_cmp_lt_f32_e64 s[0:1], |v27|, s27
	s_nop 1
	v_cndmask_b32_e64 v27, v27, v29, s[0:1]
	v_cndmask_b32_e32 v29, 0, v48, vcc
	s_cselect_b64 vcc, -1, 0
	s_or_b32 s17, s16, 11
	s_lshl_b32 s0, s17, 6
	s_add_i32 s0, s0, 0
	v_sub_f32_e32 v27, v27, v29
	v_mov_b32_e32 v42, s0
	v_sub_f32_e32 v27, v28, v27
	ds_read_b128 v[28:31], v42
	ds_read_b128 v[32:35], v42 offset:16
	ds_read_b128 v[38:41], v42 offset:32
	ds_read_b128 v[42:45], v42 offset:48
	v_mul_f32_e32 v27, 0x3d800000, v27
	s_waitcnt lgkmcnt(3)
	v_fma_f32 v28, v1, v28, v16
	v_fmac_f32_e32 v28, v0, v29
	v_fmac_f32_e32 v28, v5, v30
	v_fmac_f32_e32 v28, v4, v31
	s_waitcnt lgkmcnt(2)
	v_fmac_f32_e32 v28, v3, v32
	v_fmac_f32_e32 v28, v2, v33
	v_fmac_f32_e32 v28, v7, v34
	v_fmac_f32_e32 v28, v6, v35
	s_waitcnt lgkmcnt(1)
	v_fmac_f32_e32 v28, v9, v38
	v_fmac_f32_e32 v28, v8, v39
	v_fmac_f32_e32 v28, v14, v40
	v_fmac_f32_e32 v28, v12, v41
	s_waitcnt lgkmcnt(0)
	v_fmac_f32_e32 v28, v11, v42
	v_fmac_f32_e32 v28, v10, v43
	v_fmac_f32_e32 v28, v15, v44
	v_fmac_f32_e32 v28, v13, v45
	v_min_f32_e32 v29, 0, v28
	v_mul_f32_e64 v28, |v28|, s31
	v_exp_f32_e32 v28, v28
	v_cndmask_b32_e32 v27, 0, v27, vcc
	s_cmp_lt_i32 s17, s84
	v_add_f32_e32 v27, v26, v27
	v_add_f32_e32 v28, 1.0, v28
	v_cmp_gt_f32_e32 vcc, s38, v28
	s_nop 1
	v_cndmask_b32_e64 v30, 0, 32, vcc
	v_ldexp_f32 v28, v28, v30
	v_log_f32_e32 v28, v28
	s_nop 0
	v_mul_f32_e32 v30, 0x3f317217, v28
	v_fma_f32 v30, v28, s39, -v30
	v_fmac_f32_e32 v30, 0x3377d1cf, v28
	v_fmac_f32_e32 v30, 0x3f317217, v28
	v_cmp_lt_f32_e64 s[0:1], |v28|, s27
	s_nop 1
	v_cndmask_b32_e64 v28, v28, v30, s[0:1]
	v_cndmask_b32_e32 v30, 0, v48, vcc
	s_cselect_b64 vcc, -1, 0
	s_or_b32 s17, s16, 12
	s_lshl_b32 s0, s17, 6
	v_sub_f32_e32 v28, v28, v30
	s_add_i32 s0, s0, 0
	v_sub_f32_e32 v28, v29, v28
	v_mov_b32_e32 v29, s0
	ds_read_b128 v[30:33], v29
	ds_read_b128 v[38:41], v29 offset:16
	ds_read_b128 v[42:45], v29 offset:32
	ds_read_b128 v[52:55], v29 offset:48
	v_mul_f32_e32 v28, 0x3d800000, v28
	s_waitcnt lgkmcnt(3)
	v_fma_f32 v29, v1, v30, v16
	v_fmac_f32_e32 v29, v0, v31
	v_fmac_f32_e32 v29, v5, v32
	v_fmac_f32_e32 v29, v4, v33
	s_waitcnt lgkmcnt(2)
	v_fmac_f32_e32 v29, v3, v38
	v_fmac_f32_e32 v29, v2, v39
	v_fmac_f32_e32 v29, v7, v40
	v_fmac_f32_e32 v29, v6, v41
	s_waitcnt lgkmcnt(1)
	v_fmac_f32_e32 v29, v9, v42
	v_fmac_f32_e32 v29, v8, v43
	v_fmac_f32_e32 v29, v14, v44
	v_fmac_f32_e32 v29, v12, v45
	s_waitcnt lgkmcnt(0)
	v_fmac_f32_e32 v29, v11, v52
	v_fmac_f32_e32 v29, v10, v53
	v_fmac_f32_e32 v29, v15, v54
	v_fmac_f32_e32 v29, v13, v55
	v_min_f32_e32 v30, 0, v29
	v_mul_f32_e64 v29, |v29|, s31
	v_exp_f32_e32 v29, v29
	v_cndmask_b32_e32 v28, 0, v28, vcc
	s_cmp_lt_i32 s17, s84
	v_add_f32_e32 v28, v27, v28
	v_add_f32_e32 v29, 1.0, v29
	v_cmp_gt_f32_e32 vcc, s38, v29
	s_nop 1
	v_cndmask_b32_e64 v31, 0, 32, vcc
	v_ldexp_f32 v29, v29, v31
	v_log_f32_e32 v29, v29
	s_nop 0
	v_mul_f32_e32 v31, 0x3f317217, v29
	v_fma_f32 v31, v29, s39, -v31
	v_fmac_f32_e32 v31, 0x3377d1cf, v29
	v_fmac_f32_e32 v31, 0x3f317217, v29
	v_cmp_lt_f32_e64 s[0:1], |v29|, s27
	s_nop 1
	v_cndmask_b32_e64 v29, v29, v31, s[0:1]
	v_cndmask_b32_e32 v31, 0, v48, vcc
	s_cselect_b64 vcc, -1, 0
	s_or_b32 s17, s16, 13
	s_lshl_b32 s0, s17, 6
	s_add_i32 s0, s0, 0
	v_sub_f32_e32 v29, v29, v31
	v_mov_b32_e32 v34, s0
	v_sub_f32_e32 v29, v30, v29
	ds_read_b128 v[30:33], v34
	ds_read_b128 v[38:41], v34 offset:16
	ds_read_b128 v[42:45], v34 offset:32
	ds_read_b128 v[52:55], v34 offset:48
	v_mul_f32_e32 v29, 0x3d800000, v29
	s_waitcnt lgkmcnt(3)
	v_fma_f32 v30, v1, v30, v16
	v_fmac_f32_e32 v30, v0, v31
	v_fmac_f32_e32 v30, v5, v32
	v_fmac_f32_e32 v30, v4, v33
	s_waitcnt lgkmcnt(2)
	v_fmac_f32_e32 v30, v3, v38
	v_fmac_f32_e32 v30, v2, v39
	v_fmac_f32_e32 v30, v7, v40
	v_fmac_f32_e32 v30, v6, v41
	s_waitcnt lgkmcnt(1)
	v_fmac_f32_e32 v30, v9, v42
	v_fmac_f32_e32 v30, v8, v43
	v_fmac_f32_e32 v30, v14, v44
	v_fmac_f32_e32 v30, v12, v45
	s_waitcnt lgkmcnt(0)
	v_fmac_f32_e32 v30, v11, v52
	v_fmac_f32_e32 v30, v10, v53
	v_fmac_f32_e32 v30, v15, v54
	v_fmac_f32_e32 v30, v13, v55
	v_min_f32_e32 v31, 0, v30
	v_mul_f32_e64 v30, |v30|, s31
	v_exp_f32_e32 v30, v30
	v_cndmask_b32_e32 v29, 0, v29, vcc
	s_cmp_lt_i32 s17, s84
	v_add_f32_e32 v29, v28, v29
	v_add_f32_e32 v30, 1.0, v30
	v_cmp_gt_f32_e32 vcc, s38, v30
	s_nop 1
	v_cndmask_b32_e64 v32, 0, 32, vcc
	v_ldexp_f32 v30, v30, v32
	v_log_f32_e32 v30, v30
	s_nop 0
	v_mul_f32_e32 v32, 0x3f317217, v30
	v_fma_f32 v32, v30, s39, -v32
	v_fmac_f32_e32 v32, 0x3377d1cf, v30
	v_fmac_f32_e32 v32, 0x3f317217, v30
	v_cmp_lt_f32_e64 s[0:1], |v30|, s27
	s_nop 1
	v_cndmask_b32_e64 v30, v30, v32, s[0:1]
	v_cndmask_b32_e32 v32, 0, v48, vcc
	s_cselect_b64 vcc, -1, 0
	s_or_b32 s17, s16, 14
	s_lshl_b32 s0, s17, 6
	v_sub_f32_e32 v30, v30, v32
	s_add_i32 s0, s0, 0
	v_sub_f32_e32 v30, v31, v30
	v_mov_b32_e32 v31, s0
	ds_read_b128 v[32:35], v31
	ds_read_b128 v[38:41], v31 offset:16
	ds_read_b128 v[42:45], v31 offset:32
	ds_read_b128 v[52:55], v31 offset:48
	v_mul_f32_e32 v30, 0x3d800000, v30
	s_waitcnt lgkmcnt(3)
; __device__ __forceinline__ float bf2f(bf16_t b) { return __uint_as_float(((unsigned)b) << 16); }
; __device__ __forceinline__ void gla_gate(unsigned char* lds, const bf16_t* P, const float* wgu, const float* bgt, int row0, int nvalid, int h, float (&bc)[16], float& blast) {
;     ...
;     for (int i = 0; i < 16; ++i) {
;         const int t = tq * 16 + i; float x = bg;
;         const f32x4* g4 = (const f32x4*)(gl + t * 16);
; #pragma unroll
;         for (int r4 = 0; r4 < 4; ++r4) { const f32x4 gv = g4[r4];
; #pragma unroll
;             for (int e = 0; e < 4; ++e) x += gv[e] * wg[4 * r4 + e]; }
;         float lg = fminf(x, 0.f) - __logf(1.f + __expf(-fabsf(x)));
;         lg = (t < nvalid) ? lg * (1.f / 16.f) : 0.f;
;         run += lg; bc[i] = run;
;     }
;     part[tq * 128 + kd] = run;
;     __syncthreads();
;     float off = 0.f, tot = 0.f;
; #pragma unroll
;     for (int q = 0; q < 4; ++q) { const float pv = part[q * 128 + kd]; tot += pv; if (q < tq) off += pv; }
; #pragma unroll
;     for (int i = 0; i < 16; ++i) bc[i] += off;
;     blast = tot;
; }
; __device__ __forceinline__ void gla_c_item(unsigned char* lds, const Params& p, int item, bool dry) {
;     ...
;     { const bf16_t* qp = P + (size_t)(row0 + tq * 16) * NPROJ + h * 128;
; #pragma unroll
;     for (int i = 0; i < 16; ++i) { const int t = tq * 16 + i;
;         float qv = 0.f, kv = 0.f;
;         if (t < nvalid) { qv = bf2f(qp[i * NPROJ + C_QA + kd]); kv = bf2f(qp[i * NPROJ + C_KA + kd]); }
	v_fma_f32 v31, v1, v32, v16
	v_fmac_f32_e32 v31, v0, v33
	v_fmac_f32_e32 v31, v5, v34
	v_fmac_f32_e32 v31, v4, v35
	s_waitcnt lgkmcnt(2)
	v_fmac_f32_e32 v31, v3, v38
	v_fmac_f32_e32 v31, v2, v39
	v_fmac_f32_e32 v31, v7, v40
	v_fmac_f32_e32 v31, v6, v41
	s_waitcnt lgkmcnt(1)
	v_fmac_f32_e32 v31, v9, v42
	v_fmac_f32_e32 v31, v8, v43
	v_fmac_f32_e32 v31, v14, v44
	v_fmac_f32_e32 v31, v12, v45
	s_waitcnt lgkmcnt(0)
	v_fmac_f32_e32 v31, v11, v52
	v_fmac_f32_e32 v31, v10, v53
	v_fmac_f32_e32 v31, v15, v54
	v_fmac_f32_e32 v31, v13, v55
	v_min_f32_e32 v32, 0, v31
	v_mul_f32_e64 v31, |v31|, s31
	v_exp_f32_e32 v31, v31
	v_cndmask_b32_e32 v30, 0, v30, vcc
	s_cmp_lt_i32 s17, s84
	v_add_f32_e32 v30, v29, v30
	v_add_f32_e32 v31, 1.0, v31
	v_cmp_gt_f32_e32 vcc, s38, v31
	s_nop 1
	v_cndmask_b32_e64 v33, 0, 32, vcc
	v_ldexp_f32 v31, v31, v33
	v_log_f32_e32 v31, v31
	s_nop 0
	v_mul_f32_e32 v33, 0x3f317217, v31
	v_fma_f32 v33, v31, s39, -v33
	v_fmac_f32_e32 v33, 0x3377d1cf, v31
	v_fmac_f32_e32 v33, 0x3f317217, v31
	v_cmp_lt_f32_e64 s[0:1], |v31|, s27
	s_nop 1
	v_cndmask_b32_e64 v31, v31, v33, s[0:1]
	v_cndmask_b32_e32 v33, 0, v48, vcc
	s_cselect_b64 vcc, -1, 0
	s_or_b32 s16, s16, 15
	s_lshl_b32 s0, s16, 6
	s_add_i32 s0, s0, 0
	v_sub_f32_e32 v31, v31, v33
	v_mov_b32_e32 v46, s0
	v_sub_f32_e32 v31, v32, v31
	ds_read_b128 v[32:35], v46
	ds_read_b128 v[38:41], v46 offset:16
	ds_read_b128 v[42:45], v46 offset:32
	ds_read_b128 v[52:55], v46 offset:48
	v_mul_f32_e32 v31, 0x3d800000, v31
	s_waitcnt lgkmcnt(3)
	v_fmac_f32_e32 v16, v1, v32
	v_fmac_f32_e32 v16, v0, v33
	v_fmac_f32_e32 v16, v5, v34
	v_fmac_f32_e32 v16, v4, v35
	s_waitcnt lgkmcnt(2)
	v_fmac_f32_e32 v16, v3, v38
	v_fmac_f32_e32 v16, v2, v39
	v_fmac_f32_e32 v16, v7, v40
	v_fmac_f32_e32 v16, v6, v41
	s_waitcnt lgkmcnt(1)
	v_fmac_f32_e32 v16, v9, v42
	v_fmac_f32_e32 v16, v8, v43
	v_fmac_f32_e32 v16, v14, v44
	v_fmac_f32_e32 v16, v12, v45
	s_waitcnt lgkmcnt(0)
	v_fmac_f32_e32 v16, v11, v52
	v_fmac_f32_e32 v16, v10, v53
	v_fmac_f32_e32 v16, v15, v54
	v_fmac_f32_e32 v16, v13, v55
	v_mul_f32_e64 v1, |v16|, s31
	v_exp_f32_e32 v1, v1
	v_cndmask_b32_e32 v31, 0, v31, vcc
	v_min_f32_e32 v0, 0, v16
	s_cmp_lt_i32 s16, s84
	v_add_f32_e32 v1, 1.0, v1
	v_cmp_gt_f32_e32 vcc, s38, v1
	v_add_f32_e32 v31, v30, v31
	v_mov_b32_e32 v16, v250
	v_cndmask_b32_e64 v2, 0, 32, vcc
	v_ldexp_f32 v1, v1, v2
	v_log_f32_e32 v1, v1
	v_mov_b32_e32 v6, 0
	v_mov_b32_e32 v7, 0
	v_mov_b32_e32 v8, 0
	v_mul_f32_e32 v2, 0x3f317217, v1
	v_fma_f32 v2, v1, s39, -v2
	v_fmac_f32_e32 v2, 0x3377d1cf, v1
	v_fmac_f32_e32 v2, 0x3f317217, v1
	v_cmp_lt_f32_e64 s[0:1], |v1|, s27
	s_nop 1
	v_cndmask_b32_e64 v1, v1, v2, s[0:1]
	v_cndmask_b32_e32 v2, 0, v48, vcc
	v_sub_f32_e32 v1, v1, v2
	v_sub_f32_e32 v0, v0, v1
	s_cselect_b64 vcc, -1, 0
	s_and_b32 s0, s90, 0x3fffff80
	v_mul_f32_e32 v0, 0x3d800000, v0
	s_lshl_b32 s0, s0, 2
	v_cndmask_b32_e32 v0, 0, v0, vcc
	s_add_i32 s0, s0, 0
	v_add_f32_e32 v4, v31, v0
	v_add_u32_e32 v0, s0, v36
	ds_write_b32 v0, v4 offset:4096
	v_add_u32_e32 v0, 0, v36
	s_waitcnt lgkmcnt(0)
	s_barrier
	ds_read2st64_b32 v[2:3], v0 offset0:16 offset1:18
	ds_read2st64_b32 v[0:1], v0 offset0:20 offset1:22
	s_nop 0
	v_readfirstlane_b32 s17, v16
	s_ashr_i32 s18, s17, 3
	s_and_b32 s19, s18, -16
	s_add_i32 s0, s19, s75
	s_mul_hi_i32 s1, s0, 0x3200
	s_mulk_i32 s0, 0x3200
	s_add_u32 s0, s56, s0
	s_addc_u32 s1, s57, s1
	s_lshl_b32 s16, s15, 8
	s_add_u32 s0, s0, s16
	v_and_b32_e32 v5, 0x7f, v16
	s_addc_u32 s1, s1, 0
	s_cmp_ge_i32 s19, s84
	v_lshlrev_b32_e32 v36, 1, v5
	s_mov_b32 s98, s0
	s_mov_b32 s99, s1
	global_load_ushort v200, v36, s[98:99]
	global_load_ushort v201, v36, s[98:99] offset:1024
	s_add_u32 s98, s98, 0x3200
	s_addc_u32 s99, s99, 0
	global_load_ushort v202, v36, s[98:99]
	global_load_ushort v203, v36, s[98:99] offset:1024
	s_add_u32 s98, s98, 0x3200
	s_addc_u32 s99, s99, 0
	global_load_ushort v204, v36, s[98:99]
	global_load_ushort v205, v36, s[98:99] offset:1024
	s_add_u32 s98, s98, 0x3200
	s_addc_u32 s99, s99, 0
	global_load_ushort v206, v36, s[98:99]
	global_load_ushort v207, v36, s[98:99] offset:1024
	s_add_u32 s98, s98, 0x3200
	s_addc_u32 s99, s99, 0
	global_load_ushort v208, v36, s[98:99]
	global_load_ushort v209, v36, s[98:99] offset:1024
	s_add_u32 s98, s98, 0x3200
	s_addc_u32 s99, s99, 0
	global_load_ushort v210, v36, s[98:99]
	global_load_ushort v211, v36, s[98:99] offset:1024
	s_add_u32 s98, s98, 0x3200
	s_addc_u32 s99, s99, 0
	global_load_ushort v212, v36, s[98:99]
	global_load_ushort v213, v36, s[98:99] offset:1024
	s_add_u32 s98, s98, 0x3200
	s_addc_u32 s99, s99, 0
	global_load_ushort v214, v36, s[98:99]
	global_load_ushort v215, v36, s[98:99] offset:1024
	s_add_u32 s98, s98, 0x3200
	s_addc_u32 s99, s99, 0
	global_load_ushort v200, v36, s[98:99]
	global_load_ushort v201, v36, s[98:99] offset:1024
	s_add_u32 s98, s98, 0x3200
	s_addc_u32 s99, s99, 0
	global_load_ushort v202, v36, s[98:99]
	global_load_ushort v203, v36, s[98:99] offset:1024
	s_add_u32 s98, s98, 0x3200
	s_addc_u32 s99, s99, 0
	global_load_ushort v204, v36, s[98:99]
	global_load_ushort v205, v36, s[98:99] offset:1024
	s_add_u32 s98, s98, 0x3200
	s_addc_u32 s99, s99, 0
	global_load_ushort v206, v36, s[98:99]
	global_load_ushort v207, v36, s[98:99] offset:1024
	s_add_u32 s98, s98, 0x3200
	s_addc_u32 s99, s99, 0
	global_load_ushort v208, v36, s[98:99]
	global_load_ushort v209, v36, s[98:99] offset:1024
	s_add_u32 s98, s98, 0x3200
	s_addc_u32 s99, s99, 0
	global_load_ushort v210, v36, s[98:99]
	global_load_ushort v211, v36, s[98:99] offset:1024
	s_add_u32 s98, s98, 0x3200
	s_addc_u32 s99, s99, 0
	global_load_ushort v212, v36, s[98:99]
	global_load_ushort v213, v36, s[98:99] offset:1024
	s_add_u32 s98, s98, 0x3200
	s_addc_u32 s99, s99, 0
	global_load_ushort v214, v36, s[98:99]
	global_load_ushort v215, v36, s[98:99] offset:1024
	s_cmp_ge_i32 s19, s84
	s_cbranch_scc1 .LBB0_971
	global_load_ushort v7, v36, s[0:1] offset:1024
	global_load_ushort v8, v36, s[0:1]
	s_waitcnt vmcnt(1)
	v_lshlrev_b32_e32 v7, 16, v7
	s_waitcnt vmcnt(0)
	v_lshlrev_b32_e32 v8, 16, v8

; __global__ void __launch_bounds__(512, 2) mk_fwd(Params p) {
	.amdhsa_kernel _Z6mk_fwd6Params
		.amdhsa_group_segment_fixed_size 0
		.amdhsa_private_segment_fixed_size 0
		.amdhsa_kernarg_size 504
		.amdhsa_user_sgpr_count 2
		.amdhsa_user_sgpr_dispatch_ptr 0
		.amdhsa_user_sgpr_queue_ptr 0
		.amdhsa_user_sgpr_kernarg_segment_ptr 1
		.amdhsa_user_sgpr_dispatch_id 0
		.amdhsa_user_sgpr_kernarg_preload_length 0
		.amdhsa_user_sgpr_kernarg_preload_offset 0
		.amdhsa_user_sgpr_private_segment_size 0
		.amdhsa_uses_dynamic_stack 0
		.amdhsa_enable_private_segment 0
		.amdhsa_system_sgpr_workgroup_id_x 1
		.amdhsa_system_sgpr_workgroup_id_y 0
		.amdhsa_system_sgpr_workgroup_id_z 0
		.amdhsa_system_sgpr_workgroup_info 0
		.amdhsa_system_vgpr_workitem_id 2
		.amdhsa_next_free_vgpr 256
		.amdhsa_next_free_sgpr 102
		.amdhsa_accum_offset 256
		.amdhsa_reserve_vcc 1
		.amdhsa_float_round_mode_32 0
		.amdhsa_float_round_mode_16_64 0
		.amdhsa_float_denorm_mode_32 3
		.amdhsa_float_denorm_mode_16_64 3
		.amdhsa_dx10_clamp 1
		.amdhsa_ieee_mode 1
		.amdhsa_fp16_overflow 0
		.amdhsa_tg_split 0
		.amdhsa_exception_fp_ieee_invalid_op 0
		.amdhsa_exception_fp_denorm_src 0
		.amdhsa_exception_fp_ieee_div_zero 0
		.amdhsa_exception_fp_ieee_overflow 0
		.amdhsa_exception_fp_ieee_underflow 0
		.amdhsa_exception_fp_ieee_inexact 0
		.amdhsa_exception_int_div_zero 0
	.end_amdhsa_kernel

; __global__ void __launch_bounds__(512, 2) mk_fwd(Params p) {
amdhsa.kernels:
  - .agpr_count:     0
    .args:
      - .offset:         0
        .size:           248
        .value_kind:     by_value
      - .offset:         248
        .size:           4
        .value_kind:     hidden_block_count_x
      - .offset:         252
        .size:           4
        .value_kind:     hidden_block_count_y
      - .offset:         256
        .size:           4
        .value_kind:     hidden_block_count_z
      - .offset:         260
        .size:           2
        .value_kind:     hidden_group_size_x
      - .offset:         262
        .size:           2
        .value_kind:     hidden_group_size_y
      - .offset:         264
        .size:           2
        .value_kind:     hidden_group_size_z
      - .offset:         266
        .size:           2
        .value_kind:     hidden_remainder_x
      - .offset:         268
        .size:           2
        .value_kind:     hidden_remainder_y
      - .offset:         270
        .size:           2
        .value_kind:     hidden_remainder_z
      - .offset:         288
        .size:           8
        .value_kind:     hidden_global_offset_x
      - .offset:         296
        .size:           8
        .value_kind:     hidden_global_offset_y
      - .offset:         304
        .size:           8
        .value_kind:     hidden_global_offset_z
      - .offset:         312
        .size:           2
        .value_kind:     hidden_grid_dims
      - .offset:         336
        .size:           8
        .value_kind:     hidden_multigrid_sync_arg
      - .offset:         368
        .size:           4
        .value_kind:     hidden_dynamic_lds_size
    .group_segment_fixed_size: 0
    .kernarg_segment_align: 8
    .kernarg_segment_size: 504
    .language:       OpenCL C
    .language_version:
      - 2
      - 0
    .max_flat_workgroup_size: 512
    .name:           _Z6mk_fwd6Params
    .private_segment_fixed_size: 0
    .sgpr_count:     108
    .sgpr_spill_count: 298
    .symbol:         _Z6mk_fwd6Params.kd
    .uniform_work_group_size: 1
    .uses_dynamic_stack: false
    .vgpr_count:     256
    .vgpr_spill_count: 0
    .wavefront_size: 64
